# attn dense loops: cross-half max exchange only on the rare rescale path (bpermute removed from fast path)
# speedup vs baseline: 1.0162x; 1.0162x over previous
; #define MFMA(a, b, c) __builtin_amdgcn_mfma_f32_32x32x16_bf16((a), (b), (c), 0, 0, 0)
; template <int DQK, bool BAND, int QT> ...
;     ...
;       f32x16 s[2][QT];
; #pragma unroll
;       for (int a = 0; a < 2; ++a)
; #pragma unroll
;         for (int b = 0; b < QT; ++b)
; #pragma unroll
;           for (int r = 0; r < 16; ++r) s[a][b][r] = 0.f;
; #pragma unroll
;       for (int ks = 0; ks < NKS; ++ks) {
;         const bf16x8 k0 = *(const bf16x8*)(st + k_rd + ks * 32);
;         const bf16x8 k1 = *(const bf16x8*)(st + k_rd + 32 * KROW + ks * 32);
; #pragma unroll
;         for (int qt = 0; qt < QT; ++qt) {
;           s[0][qt] = MFMA(k0, qf[qt][ks], s[0][qt]);
;           s[1][qt] = MFMA(k1, qf[qt][ks], s[1][qt]);
;         }
;       }
;       __builtin_amdgcn_s_setprio(3);
;       bf16x8 pf[QT][4];
;       const float cc = BAND ? 1.0f : scale_log2;
;       const float th = BAND ? 8.0f : 8.0f / scale_log2;
; #pragma unroll
;       for (int qt = 0; qt < QT; ++qt) {
;         if (BAND) {
; #pragma unroll
;           for (int a = 0; a < 2; ++a)
; #pragma unroll
;             for (int r = 0; r < 16; ++r) {
;               const int kidx = kt + 32 * a + (r & 7) + 8 * h + 16 * (r >> 3);
;               const int rel = kidx - (qw0 + qt * 32 + ql);
;               const bool ok = (rel >= -64) && (rel <= 64);
;               const int bi = ok ? rel + 64 : 0;
;               s[a][qt][r] = ok ? fmaf(s[a][qt][r], scale_log2, bias_l[bi]) : -1e30f;
;             }
;         }
;         float mx = s[0][qt][0];
; #pragma unroll
;         for (int r = 1; r < 16; ++r) mx = fmaxf(mx, s[0][qt][r]);
; #pragma unroll
;         for (int r = 0; r < 16; ++r) mx = fmaxf(mx, s[1][qt][r]);
;         mx = fmaxf(mx, __shfl_xor(mx, 32));
;         if (__builtin_amdgcn_ballot_w64(mx > m[qt] + th) != 0) {
;           const float mn = fmaxf(m[qt], mx);
;           const float alpha = __builtin_amdgcn_exp2f((m[qt] - mn) * cc);
;           m[qt] = mn;
;           l[qt] *= alpha;
; #pragma unroll
;           for (int r = 0; r < 16; ++r) { o[0][qt][r] *= alpha; o[1][qt][r] *= alpha; }
;         }
.LBB0_831:
	s_bitcmp1_b32 s1, 0
	s_cselect_b32 s7, 0x4800, 0
	s_add_i32 s7, s7, 0
	v_add3_u32 v203, s7, v185, v0
	ds_read_b128 v[98:101], v203 offset:4608
	ds_read_b128 v[102:105], v203
	ds_read_b128 v[206:209], v203 offset:32
	ds_read_b128 v[210:213], v203 offset:4640
	s_waitcnt vmcnt(7) lgkmcnt(3)
	v_mfma_f32_32x32x16_bf16 v[66:81], v[98:101], v[146:149], 0
	s_waitcnt lgkmcnt(2)
	v_mfma_f32_32x32x16_bf16 v[82:97], v[102:105], v[146:149], 0
	s_waitcnt vmcnt(3)
	v_mfma_f32_32x32x16_bf16 v[114:129], v[102:105], v[162:165], 0
	v_mfma_f32_32x32x16_bf16 v[98:113], v[98:101], v[162:165], 0
	s_waitcnt lgkmcnt(1)
	v_mfma_f32_32x32x16_bf16 v[82:97], v[206:209], v[150:153], v[82:97]
	s_waitcnt lgkmcnt(0)
	v_mfma_f32_32x32x16_bf16 v[66:81], v[210:213], v[150:153], v[66:81]
	s_waitcnt vmcnt(2)
	v_mfma_f32_32x32x16_bf16 v[114:129], v[206:209], v[166:169], v[114:129]
	v_mfma_f32_32x32x16_bf16 v[98:113], v[210:213], v[166:169], v[98:113]
	ds_read_b128 v[206:209], v203 offset:64
	ds_read_b128 v[210:213], v203 offset:4672
	s_waitcnt lgkmcnt(1)
	v_mfma_f32_32x32x16_bf16 v[82:97], v[206:209], v[154:157], v[82:97]
	s_waitcnt lgkmcnt(0)
	v_mfma_f32_32x32x16_bf16 v[66:81], v[210:213], v[154:157], v[66:81]
	s_waitcnt vmcnt(1)
	v_mfma_f32_32x32x16_bf16 v[114:129], v[206:209], v[170:173], v[114:129]
	v_mfma_f32_32x32x16_bf16 v[98:113], v[210:213], v[170:173], v[98:113]
	ds_read_b128 v[206:209], v203 offset:96
	ds_read_b128 v[210:213], v203 offset:4704
	s_waitcnt lgkmcnt(1)
	v_mfma_f32_32x32x16_bf16 v[82:97], v[206:209], v[158:161], v[82:97]
	s_waitcnt lgkmcnt(0)
	v_mfma_f32_32x32x16_bf16 v[66:81], v[210:213], v[158:161], v[66:81]
	s_waitcnt vmcnt(0)
	v_mfma_f32_32x32x16_bf16 v[114:129], v[206:209], v[174:177], v[114:129]
	v_mfma_f32_32x32x16_bf16 v[98:113], v[210:213], v[174:177], v[98:113]
	s_setprio 3
	s_nop 5
	v_max_f32_e32 v203, v82, v83
	v_max3_f32 v203, v203, v84, v85
	v_max3_f32 v203, v203, v86, v87
	v_max3_f32 v203, v203, v88, v89
	v_max3_f32 v203, v203, v90, v91
	v_max3_f32 v203, v203, v92, v93
	v_max3_f32 v203, v203, v94, v95
	v_max3_f32 v203, v203, v96, v97
	v_max3_f32 v203, v203, v66, v67
	v_max3_f32 v203, v203, v68, v69
	v_max3_f32 v203, v203, v70, v71
	v_max3_f32 v203, v203, v72, v73
	v_max3_f32 v203, v203, v74, v75
	v_max3_f32 v203, v203, v76, v77
	v_max3_f32 v203, v203, v78, v79
	v_max3_f32 v203, v203, v80, v81
	v_add_f32_e32 v204, 0x42317218, v197
	v_cmp_gt_f32_e32 vcc, v203, v204
	s_cbranch_vccz .LBB0_833
	ds_bpermute_b32 v204, v179, v203
	s_waitcnt lgkmcnt(0)
	v_max_f32_e32 v204, v204, v204
	v_max_f32_e32 v203, v203, v204
	v_max_f32_e32 v203, v203, v203
	v_max_f32_e32 v204, v197, v197
	v_max_f32_e32 v203, v204, v203
	v_sub_f32_e32 v197, v197, v203
	v_mul_f32_e32 v197, 0x3e38aa3b, v197
	v_exp_f32_e32 v204, v197
	v_mov_b32_e32 v197, v203
	v_mul_f32_e32 v187, v187, v204
	v_pk_mul_f32 v[64:65], v[64:65], v[204:205] op_sel_hi:[1,0]
	v_pk_mul_f32 v[62:63], v[62:63], v[204:205] op_sel_hi:[1,0]
	v_pk_mul_f32 v[60:61], v[60:61], v[204:205] op_sel_hi:[1,0]
	v_pk_mul_f32 v[58:59], v[58:59], v[204:205] op_sel_hi:[1,0]
	v_pk_mul_f32 v[56:57], v[56:57], v[204:205] op_sel_hi:[1,0]
	v_pk_mul_f32 v[54:55], v[54:55], v[204:205] op_sel_hi:[1,0]
	v_pk_mul_f32 v[52:53], v[52:53], v[204:205] op_sel_hi:[1,0]
	v_pk_mul_f32 v[50:51], v[50:51], v[204:205] op_sel_hi:[1,0]
	v_pk_mul_f32 v[48:49], v[48:49], v[204:205] op_sel_hi:[1,0]
	v_pk_mul_f32 v[46:47], v[46:47], v[204:205] op_sel_hi:[1,0]
	v_pk_mul_f32 v[44:45], v[44:45], v[204:205] op_sel_hi:[1,0]
	v_pk_mul_f32 v[42:43], v[42:43], v[204:205] op_sel_hi:[1,0]
	v_pk_mul_f32 v[40:41], v[40:41], v[204:205] op_sel_hi:[1,0]
	v_pk_mul_f32 v[38:39], v[38:39], v[204:205] op_sel_hi:[1,0]
	v_pk_mul_f32 v[36:37], v[36:37], v[204:205] op_sel_hi:[1,0]
	v_pk_mul_f32 v[34:35], v[34:35], v[204:205] op_sel_hi:[1,0]

; #define MFMA(a, b, c) __builtin_amdgcn_mfma_f32_32x32x16_bf16((a), (b), (c), 0, 0, 0)
; template <int DQK, bool BAND, int QT> ...
;     ...
;       f32x16 s[2][QT];
; #pragma unroll
;       for (int a = 0; a < 2; ++a)
; #pragma unroll
;         for (int b = 0; b < QT; ++b)
; #pragma unroll
;           for (int r = 0; r < 16; ++r) s[a][b][r] = 0.f;
; #pragma unroll
;       for (int ks = 0; ks < NKS; ++ks) {
;         const bf16x8 k0 = *(const bf16x8*)(st + k_rd + ks * 32);
;         const bf16x8 k1 = *(const bf16x8*)(st + k_rd + 32 * KROW + ks * 32);
; #pragma unroll
;         for (int qt = 0; qt < QT; ++qt) {
;           s[0][qt] = MFMA(k0, qf[qt][ks], s[0][qt]);
;           s[1][qt] = MFMA(k1, qf[qt][ks], s[1][qt]);
;         }
;       }
;       __builtin_amdgcn_s_setprio(3);
;       bf16x8 pf[QT][4];
;       const float cc = BAND ? 1.0f : scale_log2;
;       const float th = BAND ? 8.0f : 8.0f / scale_log2;
; #pragma unroll
;       for (int qt = 0; qt < QT; ++qt) {
;         if (BAND) {
; #pragma unroll
;           for (int a = 0; a < 2; ++a)
; #pragma unroll
;             for (int r = 0; r < 16; ++r) {
;               const int kidx = kt + 32 * a + (r & 7) + 8 * h + 16 * (r >> 3);
;               const int rel = kidx - (qw0 + qt * 32 + ql);
;               const bool ok = (rel >= -64) && (rel <= 64);
;               const int bi = ok ? rel + 64 : 0;
;               s[a][qt][r] = ok ? fmaf(s[a][qt][r], scale_log2, bias_l[bi]) : -1e30f;
;             }
;         }
;         float mx = s[0][qt][0];
; #pragma unroll
;         for (int r = 1; r < 16; ++r) mx = fmaxf(mx, s[0][qt][r]);
; #pragma unroll
;         for (int r = 0; r < 16; ++r) mx = fmaxf(mx, s[1][qt][r]);
;         mx = fmaxf(mx, __shfl_xor(mx, 32));
;         if (__builtin_amdgcn_ballot_w64(mx > m[qt] + th) != 0) {
;           const float mn = fmaxf(m[qt], mx);
;           const float alpha = __builtin_amdgcn_exp2f((m[qt] - mn) * cc);
;           m[qt] = mn;
;           l[qt] *= alpha;
; #pragma unroll
;           for (int r = 0; r < 16; ++r) { o[0][qt][r] *= alpha; o[1][qt][r] *= alpha; }
;         }
.LBB0_844:
	s_bitcmp1_b32 s1, 0
	s_cselect_b32 s7, 0x5800, 0
	s_add_i32 s7, s7, 0
	v_add3_u32 v239, s7, v235, v0
	ds_read_b128 v[98:101], v239 offset:6656
	ds_read_b128 v[102:105], v239
	ds_read_b128 v[240:243], v239 offset:32
	ds_read_b128 v[244:247], v239 offset:6688
	s_waitcnt vmcnt(11) lgkmcnt(3)
	v_mfma_f32_32x32x16_bf16 v[66:81], v[98:101], v[142:145], 0
	s_waitcnt lgkmcnt(2)
	v_mfma_f32_32x32x16_bf16 v[82:97], v[102:105], v[142:145], 0
	s_waitcnt vmcnt(5)
	v_mfma_f32_32x32x16_bf16 v[114:129], v[102:105], v[174:177], 0
	v_mfma_f32_32x32x16_bf16 v[98:113], v[98:101], v[174:177], 0
	s_waitcnt lgkmcnt(1)
	v_mfma_f32_32x32x16_bf16 v[82:97], v[240:243], v[150:153], v[82:97]
	s_waitcnt lgkmcnt(0)
	v_mfma_f32_32x32x16_bf16 v[66:81], v[244:247], v[150:153], v[66:81]
	s_waitcnt vmcnt(4)
	v_mfma_f32_32x32x16_bf16 v[114:129], v[240:243], v[178:181], v[114:129]
	v_mfma_f32_32x32x16_bf16 v[98:113], v[244:247], v[178:181], v[98:113]
	ds_read_b128 v[240:243], v239 offset:64
	ds_read_b128 v[244:247], v239 offset:6720
	s_waitcnt lgkmcnt(1)
	v_mfma_f32_32x32x16_bf16 v[82:97], v[240:243], v[154:157], v[82:97]
	s_waitcnt lgkmcnt(0)
	v_mfma_f32_32x32x16_bf16 v[66:81], v[244:247], v[154:157], v[66:81]
	s_waitcnt vmcnt(3)
	v_mfma_f32_32x32x16_bf16 v[114:129], v[240:243], v[182:185], v[114:129]
	v_mfma_f32_32x32x16_bf16 v[98:113], v[244:247], v[182:185], v[98:113]
	ds_read_b128 v[240:243], v239 offset:96
	ds_read_b128 v[244:247], v239 offset:6752
	s_waitcnt lgkmcnt(1)
	v_mfma_f32_32x32x16_bf16 v[82:97], v[240:243], v[158:161], v[82:97]
	s_waitcnt lgkmcnt(0)
	v_mfma_f32_32x32x16_bf16 v[66:81], v[244:247], v[158:161], v[66:81]
	s_waitcnt vmcnt(2)
	v_mfma_f32_32x32x16_bf16 v[114:129], v[240:243], v[186:189], v[114:129]
	v_mfma_f32_32x32x16_bf16 v[98:113], v[244:247], v[186:189], v[98:113]
	ds_read_b128 v[240:243], v239 offset:128
	ds_read_b128 v[244:247], v239 offset:6784
	s_waitcnt lgkmcnt(1)
	v_mfma_f32_32x32x16_bf16 v[82:97], v[240:243], v[162:165], v[82:97]
	s_waitcnt lgkmcnt(0)
	v_mfma_f32_32x32x16_bf16 v[66:81], v[244:247], v[162:165], v[66:81]
	s_waitcnt vmcnt(1)
	v_mfma_f32_32x32x16_bf16 v[114:129], v[240:243], v[190:193], v[114:129]
	v_mfma_f32_32x32x16_bf16 v[98:113], v[244:247], v[190:193], v[98:113]
	ds_read_b128 v[240:243], v239 offset:160
	ds_read_b128 v[244:247], v239 offset:6816
	s_waitcnt lgkmcnt(1)
	v_mfma_f32_32x32x16_bf16 v[82:97], v[240:243], v[166:169], v[82:97]
	s_waitcnt lgkmcnt(0)
	v_mfma_f32_32x32x16_bf16 v[66:81], v[244:247], v[166:169], v[66:81]
	s_waitcnt vmcnt(0)
	v_mfma_f32_32x32x16_bf16 v[114:129], v[240:243], v[194:197], v[114:129]
	v_mfma_f32_32x32x16_bf16 v[98:113], v[244:247], v[194:197], v[98:113]
	s_setprio 3
	s_nop 5
	v_max_f32_e32 v239, v82, v83
	v_max3_f32 v239, v239, v84, v85
	v_max3_f32 v239, v239, v86, v87
	v_max3_f32 v239, v239, v88, v89
	v_max3_f32 v239, v239, v90, v91
	v_max3_f32 v239, v239, v92, v93
	v_max3_f32 v239, v239, v94, v95
	v_max3_f32 v239, v239, v96, v97
	v_max3_f32 v239, v239, v66, v67
	v_max3_f32 v239, v239, v68, v69
	v_max3_f32 v239, v239, v70, v71
	v_max3_f32 v239, v239, v72, v73
	v_max3_f32 v239, v239, v74, v75
	v_max3_f32 v239, v239, v76, v77
	v_max3_f32 v239, v239, v78, v79
	v_max3_f32 v239, v239, v80, v81
	v_add_f32_e32 v240, 0x4259535f, v237
	v_cmp_gt_f32_e32 vcc, v239, v240
	s_cbranch_vccz .LBB0_846
	ds_bpermute_b32 v240, v203, v239
	s_waitcnt lgkmcnt(0)
	v_max_f32_e32 v240, v240, v240
	v_max_f32_e32 v239, v239, v240
	v_max_f32_e32 v239, v239, v239
	v_max_f32_e32 v240, v237, v237
	v_max_f32_e32 v239, v240, v239
	v_sub_f32_e32 v237, v237, v239
	v_mul_f32_e32 v237, 0x3e16c740, v237
	v_exp_f32_e32 v240, v237
	v_mov_b32_e32 v237, v239
	v_mul_f32_e32 v236, v236, v240
	v_pk_mul_f32 v[64:65], v[64:65], v[240:241] op_sel_hi:[1,0]
	v_pk_mul_f32 v[62:63], v[62:63], v[240:241] op_sel_hi:[1,0]
	v_pk_mul_f32 v[60:61], v[60:61], v[240:241] op_sel_hi:[1,0]
	v_pk_mul_f32 v[58:59], v[58:59], v[240:241] op_sel_hi:[1,0]
	v_pk_mul_f32 v[56:57], v[56:57], v[240:241] op_sel_hi:[1,0]
	v_pk_mul_f32 v[54:55], v[54:55], v[240:241] op_sel_hi:[1,0]
	v_pk_mul_f32 v[52:53], v[52:53], v[240:241] op_sel_hi:[1,0]
	v_pk_mul_f32 v[50:51], v[50:51], v[240:241] op_sel_hi:[1,0]
	v_pk_mul_f32 v[48:49], v[48:49], v[240:241] op_sel_hi:[1,0]
	v_pk_mul_f32 v[46:47], v[46:47], v[240:241] op_sel_hi:[1,0]
	v_pk_mul_f32 v[44:45], v[44:45], v[240:241] op_sel_hi:[1,0]
	v_pk_mul_f32 v[42:43], v[42:43], v[240:241] op_sel_hi:[1,0]
	v_pk_mul_f32 v[40:41], v[40:41], v[240:241] op_sel_hi:[1,0]
	v_pk_mul_f32 v[38:39], v[38:39], v[240:241] op_sel_hi:[1,0]
	v_pk_mul_f32 v[36:37], v[36:37], v[240:241] op_sel_hi:[1,0]
	v_pk_mul_f32 v[34:35], v[34:35], v[240:241] op_sel_hi:[1,0]
